# xprep: waves of a workgroup staggered by 0.6 us each so load and store bursts interleave
# baseline (speedup 1.0000x reference)
.LBB0_229:
	v_readlane_b32 s6, v252, 49
	v_readlane_b32 s7, v252, 50
	s_andn2_b64 vcc, exec, s[6:7]
	s_cbranch_vccnz .LBB0_242
	v_mov_b32_e32 v1, v232
	v_readlane_b32 s1, v252, 51
	v_ashrrev_i32_e32 v0, 6, v1
	s_nop 0
	v_add_u32_e32 v2, s1, v0
	s_movk_i32 s1, 0x2200
	v_cmp_gt_i32_e32 vcc, s1, v2
	s_and_saveexec_b64 s[6:7], vcc
	s_cbranch_execz .LBB0_241
	s_load_dwordx4 s[8:11], s[88:89], 0x40
	v_lshlrev_b32_e32 v0, 1, v0
	v_readlane_b32 s1, v253, 62
	v_lshlrev_b32_e32 v28, 1, v2
	v_and_b32_e32 v2, 63, v1
	v_add_u32_e32 v31, s1, v0
	v_readlane_b32 s1, v254, 0
	v_ashrrev_i32_e32 v29, 31, v28
	v_lshlrev_b32_e32 v30, 2, v2
	v_add_u32_e32 v0, s1, v0
	v_ashrrev_i32_e32 v1, 31, v0
	v_cmp_eq_u32_e32 vcc, 0, v2
	v_lshlrev_b32_e32 v128, 4, v2
	v_lshlrev_b64 v[42:43], 11, v[0:1]
	v_lshlrev_b32_e32 v2, 3, v2
	v_lshlrev_b64 v[48:49], 11, v[28:29]
	s_waitcnt lgkmcnt(0)
	v_lshl_add_u64 v[32:33], s[10:11], 0, v[128:129]
	v_or_b32_e32 v34, 0x100, v30
	v_or_b32_e32 v36, 0x200, v30
	v_or_b32_e32 v38, 0x300, v30
	v_lshl_add_u64 v[40:41], v[0:1], 2, v[132:133]
	v_or_b32_e32 v42, v42, v2
	v_lshl_add_u64 v[44:45], v[0:1], 0, 1
	v_lshl_add_u64 v[46:47], v[28:29], 2, v[134:135]
	v_or_b32_e32 v48, v48, v2
	s_mov_b64 s[42:43], 0
	s_mov_b64 s[62:63], 0
	v_mov_b32_e32 v35, v28
	v_readfirstlane_b32 s24, v232
	s_lshr_b32 s24, s24, 6
.Lxp_stag:
	s_cmp_eq_u32 s24, 0
	s_cbranch_scc1 .Lxp_go
	s_sleep 22
	s_sub_u32 s24, s24, 1
	s_branch .Lxp_stag
.Lxp_go:
	s_branch .LBB0_233
.LBB0_232:
	s_or_b64 exec, exec, s[8:9]
	v_add_u32_e32 v35, s54, v35
	s_add_u32 s62, s62, s54
	s_movk_i32 s1, 0x43ff
	s_addc_u32 s63, s63, s55
	v_cmp_lt_i32_e64 s[38:39], s1, v35
	v_add_u32_e32 v31, s54, v31
	v_lshl_add_u64 v[40:41], v[40:41], 0, s[66:67]
	v_lshl_add_u64 v[42:43], v[42:43], 0, s[68:69]
	v_lshl_add_u64 v[46:47], v[46:47], 0, s[66:67]
	s_or_b64 s[42:43], s[38:39], s[42:43]
	v_lshl_add_u64 v[48:49], v[48:49], 0, s[68:69]
	s_andn2_b64 exec, exec, s[42:43]
	s_cbranch_execz .LBB0_241
